# chunk_scan loop: s_waitcnt vmcnt counts relaxed to the exact in-order distance (loads really 4 steps ahead), one vmcnt(0) at loop entry
# speedup vs baseline: 1.0025x; 1.0025x over previous
.LBB0_915:
	s_or_b64 exec, exec, s[12:13]
	v_lshrrev_b32_e32 v0, 4, v53
	v_and_b32_e32 v2, 15, v53
	v_bfe_u32 v55, v53, 1, 3
	v_bfe_u32 v107, v53, 4, 2
	v_lshlrev_b32_e32 v54, 7, v2
	v_bitop3_b32 v0, v0, v55, 3 bitop3:0x6c
	v_lshl_or_b32 v204, v0, 4, v54
	v_bitop3_b32 v0, v107, v55, 4 bitop3:0x36
	v_ashrrev_i32_e32 v1, 2, v53
	v_lshl_or_b32 v205, v0, 4, v54
	v_lshlrev_b32_e32 v0, 3, v107
	v_and_b32_e32 v108, -16, v1
	v_lshl_or_b32 v206, v2, 5, v0
	v_lshlrev_b32_e32 v54, 4, v2
	v_bfi_b32 v1, -16, v1, v53
	v_ashrrev_i32_e32 v53, 31, v52
	v_lshl_or_b32 v207, v107, 10, v54
	v_lshlrev_b32_e32 v208, 4, v107
	v_lshlrev_b64 v[110:111], 23, v[52:53]
	s_waitcnt lgkmcnt(0)
	s_barrier
	ds_read_b128 v[76:79], v204
	ds_read_b128 v[92:95], v204 offset:2048
	ds_read_b128 v[72:75], v205
	ds_read_b128 v[88:91], v205 offset:2048
	v_lshl_or_b32 v209, v1, 5, v0
	ds_read_b64 v[0:1], v206 offset:4096
	ds_read_b128 v[60:63], v207 offset:4608
	ds_read_b128 v[56:59], v207 offset:4864
	ds_read_b128 v[52:55], v207 offset:5120
	ds_read_b128 v[84:87], v208 offset:10816
	ds_read_b128 v[68:71], v208 offset:10880
	ds_read_b128 v[96:99], v208 offset:10752
	ds_read_b128 v[64:67], v207 offset:5376
	ds_read_b64 v[100:101], v209 offset:8704
	ds_read_b128 v[80:83], v208 offset:10944
	v_add_u32_e32 v105, v105, v106
	s_movk_i32 s12, 0x2b00
	v_mad_i64_i32 v[182:183], s[12:13], v105, s12, v[102:103]
	v_and_b32_e32 v103, 7, v104
	v_lshlrev_b32_e32 v102, 13, v107
	v_lshlrev_b32_e32 v103, 8, v103
	v_ashrrev_i32_e32 v109, 31, v108
	v_or3_b32 v110, v110, v102, v103
	v_lshl_add_u64 v[184:185], v[108:109], 2, v[110:111]
	v_mov_b32_e32 v106, 0
	v_lshl_or_b32 v184, v2, 2, v184
	s_mov_b32 s34, 0
	v_mov_b32_e32 v107, v106
	v_mov_b32_e32 v108, v106
	v_mov_b32_e32 v109, v106
	v_mov_b32_e32 v110, v106
	v_mov_b32_e32 v111, v106
	v_mov_b32_e32 v112, v106
	v_mov_b32_e32 v113, v106
	v_mov_b32_e32 v114, v106
	v_mov_b32_e32 v115, v106
	v_mov_b32_e32 v116, v106
	v_mov_b32_e32 v117, v106
	v_mov_b32_e32 v118, v106
	v_mov_b32_e32 v119, v106
	v_mov_b32_e32 v120, v106
	v_mov_b32_e32 v121, v106
	s_waitcnt vmcnt(0)
	s_branch .LBB0_917

.LBB0_917:
	s_waitcnt vmcnt(21)
	ds_write_b128 v181, v[8:11] offset:11008
	s_waitcnt vmcnt(20)
	ds_write_b128 v188, v[12:15] offset:11008
	s_and_saveexec_b64 s[12:13], s[42:43]
	ds_write_b128 v189, v[16:19] offset:11008
	s_or_b64 exec, exec, s[12:13]
	s_cmpk_gt_u32 s34, 0xfa
	v_lshl_add_u64 v[176:177], s[24:25], 0, v[182:183]
	s_cbranch_scc1 .LBB0_923
	v_add_co_u32_e32 v8, vcc, 0x4c54000, v176
	s_nop 1
	v_addc_co_u32_e32 v9, vcc, 0, v177, vcc
	v_add_co_u32_e32 v12, vcc, 0x4c55000, v176
	s_nop 1
	v_addc_co_u32_e32 v13, vcc, 0, v177, vcc
	global_load_dwordx4 v[8:11], v[8:9], off offset:1792
	s_nop 0
	global_load_dwordx4 v[12:15], v[12:13], off offset:1792
	s_and_saveexec_b64 s[12:13], s[42:43]
	s_cbranch_execz .LBB0_922
	v_add_co_u32_e32 v16, vcc, 0x4c56000, v176
	s_nop 1
	v_addc_co_u32_e32 v17, vcc, 0, v177, vcc
	global_load_dwordx4 v[16:19], v[16:17], off offset:1792

.LBB0_923:
	v_cvt_pk_bf16_f32 v122, v118, v119
	v_cvt_pk_bf16_f32 v123, v120, v121
	v_cvt_pk_bf16_f32 v124, v114, v115
	v_cvt_pk_bf16_f32 v125, v116, v117
	v_cvt_pk_bf16_f32 v130, v110, v111
	v_cvt_pk_bf16_f32 v131, v112, v113
	s_nop 0
	v_and_b32_e32 v102, 0xffff0000, v122
	v_lshlrev_b32_e32 v2, 16, v122
	v_sub_f32_e32 v102, v119, v102
	v_sub_f32_e32 v2, v118, v2
	v_cvt_pk_bf16_f32 v126, v2, v102
	v_and_b32_e32 v102, 0xffff0000, v123
	v_lshlrev_b32_e32 v2, 16, v123
	v_sub_f32_e32 v102, v121, v102
	v_sub_f32_e32 v2, v120, v2
	v_cvt_pk_bf16_f32 v127, v2, v102
	v_and_b32_e32 v102, 0xffff0000, v124
	v_lshlrev_b32_e32 v2, 16, v124
	v_sub_f32_e32 v102, v115, v102
	v_sub_f32_e32 v2, v114, v2
	v_cvt_pk_bf16_f32 v128, v2, v102
	v_and_b32_e32 v102, 0xffff0000, v125
	v_lshlrev_b32_e32 v2, 16, v125
	v_sub_f32_e32 v102, v117, v102
	v_sub_f32_e32 v2, v116, v2
	v_cvt_pk_bf16_f32 v129, v2, v102
	v_and_b32_e32 v102, 0xffff0000, v130
	v_lshlrev_b32_e32 v2, 16, v130
	v_sub_f32_e32 v102, v111, v102
	v_sub_f32_e32 v2, v110, v2
	v_cvt_pk_bf16_f32 v146, v2, v102
	v_and_b32_e32 v102, 0xffff0000, v131
	v_lshlrev_b32_e32 v2, 16, v131
	v_sub_f32_e32 v102, v113, v102
	v_sub_f32_e32 v2, v112, v2
	v_cvt_pk_bf16_f32 v147, v2, v102
	s_waitcnt lgkmcnt(14)
	v_mfma_f32_16x16x32_bf16 v[102:105], v[92:95], v[122:125], 0
	v_cvt_pk_bf16_f32 v132, v106, v107
	v_cvt_pk_bf16_f32 v133, v108, v109
	s_waitcnt lgkmcnt(3)
	v_mov_b32_e32 v160, v100
	v_mfma_f32_16x16x32_bf16 v[92:95], v[92:95], v[126:129], v[102:105]
	v_lshlrev_b32_e32 v2, 16, v132
	v_sub_f32_e32 v2, v106, v2
	v_and_b32_e32 v134, 0xffff0000, v132
	v_mfma_f32_16x16x32_bf16 v[92:95], v[88:91], v[130:133], v[92:95]
	v_sub_f32_e32 v134, v107, v134
	v_cvt_pk_bf16_f32 v148, v2, v134
	v_lshlrev_b32_e32 v2, 16, v133
	v_sub_f32_e32 v2, v108, v2
	v_and_b32_e32 v102, 0xffff0000, v133
	v_sub_f32_e32 v102, v109, v102
	v_cvt_pk_bf16_f32 v149, v2, v102
	v_mov_b32_e32 v2, v3
	v_mfma_f32_16x16x32_bf16 v[88:91], v[88:91], v[146:149], v[92:95]
	v_mov_b32_e32 v102, v3
	v_mov_b32_e32 v103, v3
	v_mov_b32_e32 v161, v101
	v_mfma_f32_16x16x32_bf16 v[92:95], v[76:79], v[122:125], 0
	v_mul_f32_e64 v98, v120, v98
	v_mul_f32_e64 v99, v121, v99
	v_pk_mul_f32 v[96:97], v[118:119], v[96:97]
	s_waitcnt lgkmcnt(0)
	v_mfma_f32_16x16x32_bf16 v[154:157], v[0:3], v[100:103], v[88:91]
	s_barrier
	s_nop 1
	ds_read_b128 v[88:91], v204 offset:11008
	ds_read_b128 v[150:153], v204 offset:13056
	v_mfma_f32_16x16x32_bf16 v[102:105], v[76:79], v[126:129], v[92:95]
	ds_read_b128 v[142:145], v205 offset:11008
	s_nop 1
	ds_read_b128 v[92:95], v205 offset:13056
	ds_read_b64 v[76:77], v206 offset:15104
	ds_read_b128 v[138:141], v207 offset:15616
	v_lshl_add_u64 v[186:187], s[24:25], 0, v[184:185]
	s_mov_b32 s12, 0x1bf07000
	v_mfma_f32_16x16x32_bf16 v[102:105], v[72:75], v[130:133], v[102:105]
	ds_read_b128 v[130:133], v207 offset:15872
	ds_read_b128 v[122:125], v207 offset:16128
	ds_read_b128 v[134:137], v208 offset:21824
	ds_read_b128 v[126:129], v208 offset:21888
	v_mfma_f32_16x16x32_bf16 v[72:75], v[72:75], v[146:149], v[102:105]
	s_nop 2
	ds_read_b128 v[100:103], v208 offset:21760
	ds_read_b128 v[118:121], v207 offset:16384
	s_nop 2
	v_xor_b32_e32 v0, 0x80000000, v72
	v_xor_b32_e32 v1, 0x80000000, v73
	v_cvt_pk_bf16_f32 v158, v0, v1
	v_xor_b32_e32 v0, 0x80000000, v74
	v_xor_b32_e32 v1, 0x80000000, v75
	v_cvt_pk_bf16_f32 v159, v0, v1
	v_lshlrev_b32_e32 v0, 16, v158
	v_and_b32_e32 v1, 0xffff0000, v158
	v_sub_f32_e64 v0, -v72, v0
	v_sub_f32_e64 v1, -v73, v1
	v_mfma_f32_16x16x32_bf16 v[96:99], v[60:63], v[158:161], v[96:99]
	v_cvt_pk_bf16_f32 v0, v0, v1
	v_lshlrev_b32_e32 v1, 16, v159
	v_and_b32_e32 v2, 0xffff0000, v159
	v_sub_f32_e64 v1, -v74, v1
	v_sub_f32_e64 v2, -v75, v2
	v_cvt_pk_bf16_f32 v1, v1, v2
	v_mov_b32_e32 v2, v3
	s_nop 1
	v_mfma_f32_16x16x32_bf16 v[96:99], v[60:63], v[0:3], v[96:99]
	v_mul_f32_e64 v62, v116, v86
	v_mul_f32_e64 v63, v117, v87
	v_pk_mul_f32 v[60:61], v[114:115], v[84:85]
	ds_read_b64 v[84:85], v209 offset:19712
	ds_read_b128 v[114:117], v208 offset:21952
	v_mfma_f32_16x16x32_bf16 v[60:63], v[56:59], v[158:161], v[60:63]
	v_mfma_f32_16x16x32_bf16 v[146:149], v[56:59], v[0:3], v[60:63]
	v_mul_f32_e64 v58, v112, v70
	v_mul_f32_e64 v59, v113, v71
	v_pk_mul_f32 v[56:57], v[110:111], v[68:69]
	s_nop 3
	v_add_co_u32_e32 v60, vcc, s12, v186
	v_mfma_f32_16x16x32_bf16 v[56:59], v[52:55], v[158:161], v[56:59]
	s_nop 0
	v_addc_co_u32_e32 v61, vcc, 0, v187, vcc
	s_mov_b32 s12, 0x1bf08000
	v_mfma_f32_16x16x32_bf16 v[110:113], v[52:55], v[0:3], v[56:59]
	v_mul_f32_e64 v54, v108, v82
	v_mul_f32_e64 v55, v109, v83
	v_pk_mul_f32 v[52:53], v[106:107], v[80:81]
	v_add_co_u32_e32 v62, vcc, s12, v186
	s_nop 0
	v_mfma_f32_16x16x32_bf16 v[52:55], v[64:67], v[158:161], v[52:55]
	v_addc_co_u32_e32 v63, vcc, 0, v187, vcc
	global_store_dword v[62:63], v154, off offset:-4096
	v_mfma_f32_16x16x32_bf16 v[106:109], v[64:67], v[0:3], v[52:55]
	global_store_dword v[60:61], v155, off offset:2048
	global_store_dword v[62:63], v156, off
	global_store_dword v[62:63], v157, off offset:2048
	s_waitcnt vmcnt(19)
	ds_write_b128 v181, v[20:23]
	s_waitcnt vmcnt(18)
	ds_write_b128 v188, v[24:27]
	s_and_saveexec_b64 s[12:13], s[42:43]
	ds_write_b128 v189, v[28:31]
	s_or_b64 exec, exec, s[12:13]
	s_cmpk_gt_u32 s34, 0xf9
	s_cbranch_scc1 .LBB0_929
	v_add_co_u32_e32 v0, vcc, 0x4c57000, v176
	s_nop 1
	v_addc_co_u32_e32 v1, vcc, 0, v177, vcc
	v_add_co_u32_e32 v24, vcc, 0x4c58000, v176
	s_nop 1
	v_addc_co_u32_e32 v25, vcc, 0, v177, vcc
	global_load_dwordx4 v[20:23], v[0:1], off offset:512
	s_nop 0
	global_load_dwordx4 v[24:27], v[24:25], off offset:512
	s_and_saveexec_b64 s[12:13], s[42:43]
	s_cbranch_execz .LBB0_928
	v_add_co_u32_e32 v0, vcc, 0x4c59000, v176
	s_nop 1
	v_addc_co_u32_e32 v1, vcc, 0, v177, vcc
	global_load_dwordx4 v[28:31], v[0:1], off offset:512

.LBB0_929:
	v_cvt_pk_bf16_f32 v52, v96, v97
	v_cvt_pk_bf16_f32 v53, v98, v99
	v_cvt_pk_bf16_f32 v54, v146, v147
	v_cvt_pk_bf16_f32 v55, v148, v149
	v_cvt_pk_bf16_f32 v60, v110, v111
	v_cvt_pk_bf16_f32 v61, v112, v113
	s_nop 0
	v_lshlrev_b32_e32 v0, 16, v52
	v_and_b32_e32 v1, 0xffff0000, v52
	v_sub_f32_e32 v0, v96, v0
	v_sub_f32_e32 v1, v97, v1
	v_cvt_pk_bf16_f32 v56, v0, v1
	v_lshlrev_b32_e32 v0, 16, v53
	v_and_b32_e32 v1, 0xffff0000, v53
	v_sub_f32_e32 v0, v98, v0
	v_sub_f32_e32 v1, v99, v1
	s_waitcnt lgkmcnt(14)
	v_mfma_f32_16x16x32_bf16 v[66:69], v[150:153], v[52:55], 0
	v_cvt_pk_bf16_f32 v57, v0, v1
	v_lshlrev_b32_e32 v0, 16, v54
	v_and_b32_e32 v1, 0xffff0000, v54
	v_sub_f32_e32 v0, v146, v0
	v_sub_f32_e32 v1, v147, v1
	v_cvt_pk_bf16_f32 v58, v0, v1
	v_lshlrev_b32_e32 v0, 16, v55
	v_and_b32_e32 v1, 0xffff0000, v55
	v_sub_f32_e32 v0, v148, v0
	v_sub_f32_e32 v1, v149, v1
	v_cvt_pk_bf16_f32 v59, v0, v1
	v_lshlrev_b32_e32 v0, 16, v60
	v_mfma_f32_16x16x32_bf16 v[68:71], v[150:153], v[56:59], v[66:69]
	v_and_b32_e32 v1, 0xffff0000, v60
	v_sub_f32_e32 v0, v110, v0
	v_sub_f32_e32 v1, v111, v1
	v_cvt_pk_bf16_f32 v64, v0, v1
	v_lshlrev_b32_e32 v0, 16, v61
	v_and_b32_e32 v1, 0xffff0000, v61
	v_cvt_pk_bf16_f32 v62, v106, v107
	v_cvt_pk_bf16_f32 v63, v108, v109
	v_sub_f32_e32 v0, v112, v0
	v_sub_f32_e32 v1, v113, v1
	s_waitcnt lgkmcnt(12)
	v_mfma_f32_16x16x32_bf16 v[68:71], v[92:95], v[60:63], v[68:71]
	v_cvt_pk_bf16_f32 v65, v0, v1
	v_lshlrev_b32_e32 v0, 16, v62
	v_and_b32_e32 v1, 0xffff0000, v62
	v_mfma_f32_16x16x32_bf16 v[52:55], v[88:91], v[52:55], 0
	v_sub_f32_e32 v0, v106, v0
	v_sub_f32_e32 v1, v107, v1
	v_cvt_pk_bf16_f32 v66, v0, v1
	v_lshlrev_b32_e32 v0, 16, v63
	v_and_b32_e32 v1, 0xffff0000, v63
	v_mov_b32_e32 v78, v3
	v_mov_b32_e32 v79, v3
	v_sub_f32_e32 v0, v108, v0
	v_sub_f32_e32 v1, v109, v1
	v_cvt_pk_bf16_f32 v67, v0, v1
	v_mfma_f32_16x16x32_bf16 v[52:55], v[88:91], v[56:59], v[52:55]
	v_mov_b32_e32 v86, v3
	v_mov_b32_e32 v87, v3
	s_mov_b32 s12, 0x1bf0f000
	v_mfma_f32_16x16x32_bf16 v[68:71], v[92:95], v[64:67], v[68:71]
	s_waitcnt lgkmcnt(6)
	v_pk_mul_f32 v[112:113], v[128:129], v[112:113]
	v_pk_mul_f32 v[110:111], v[126:127], v[110:111]
	s_waitcnt lgkmcnt(2)
	v_pk_mul_f32 v[108:109], v[116:117], v[108:109]
	v_mfma_f32_16x16x32_bf16 v[156:159], v[76:79], v[84:87], v[68:71]
	v_mul_f32_e64 v106, v114, v106
	v_mul_f32_e64 v107, v115, v107
	s_waitcnt lgkmcnt(0)
	s_barrier
	v_mfma_f32_16x16x32_bf16 v[68:71], v[142:145], v[60:63], v[52:55]
	ds_read_b128 v[76:79], v204
	ds_read_b128 v[92:95], v204 offset:2048
	ds_read_b128 v[72:75], v205
	ds_read_b128 v[88:91], v205 offset:2048
	ds_read_b64 v[104:105], v206 offset:4096
	ds_read_b128 v[60:63], v207 offset:4608
	ds_read_b128 v[56:59], v207 offset:4864
	ds_read_b128 v[52:55], v207 offset:5120
	v_mfma_f32_16x16x32_bf16 v[64:67], v[142:145], v[64:67], v[68:71]
	v_mov_b32_e32 v144, v84
	v_mov_b32_e32 v145, v85
	s_nop 0
	v_pk_mul_f32 v[70:71], v[102:103], v[98:99]
	v_pk_mul_f32 v[68:69], v[100:101], v[96:97]
	s_nop 2
	v_xor_b32_e32 v0, 0x80000000, v64
	v_xor_b32_e32 v1, 0x80000000, v65
	v_cvt_pk_bf16_f32 v142, v0, v1
	v_xor_b32_e32 v0, 0x80000000, v66
	v_xor_b32_e32 v1, 0x80000000, v67
	v_cvt_pk_bf16_f32 v143, v0, v1
	v_lshlrev_b32_e32 v0, 16, v142
	v_and_b32_e32 v1, 0xffff0000, v142
	v_sub_f32_e64 v0, -v64, v0
	v_sub_f32_e64 v1, -v65, v1
	v_mfma_f32_16x16x32_bf16 v[68:71], v[138:141], v[142:145], v[68:71]
	v_cvt_pk_bf16_f32 v0, v0, v1
	v_lshlrev_b32_e32 v1, 16, v143
	v_and_b32_e32 v2, 0xffff0000, v143
	v_sub_f32_e64 v1, -v66, v1
	v_sub_f32_e64 v2, -v67, v2
	v_pk_mul_f32 v[66:67], v[136:137], v[148:149]
	v_pk_mul_f32 v[64:65], v[134:135], v[146:147]
	v_cvt_pk_bf16_f32 v1, v1, v2
	v_mov_b32_e32 v2, v3
	v_add_co_u32_e32 v102, vcc, s12, v186
	v_mfma_f32_16x16x32_bf16 v[134:137], v[130:133], v[142:145], v[64:67]
	s_nop 0
	v_addc_co_u32_e32 v103, vcc, 0, v187, vcc
	s_mov_b32 s12, 0x1bf10000
	v_mfma_f32_16x16x32_bf16 v[110:113], v[122:125], v[142:145], v[110:113]
	v_add_co_u32_e32 v126, vcc, s12, v186
	v_mfma_f32_16x16x32_bf16 v[106:109], v[118:121], v[142:145], v[106:109]
	s_nop 0
	v_addc_co_u32_e32 v127, vcc, 0, v187, vcc
	v_mfma_f32_16x16x32_bf16 v[138:141], v[138:141], v[0:3], v[68:71]
	ds_read_b128 v[84:87], v208 offset:10816
	s_nop 1
	ds_read_b128 v[68:71], v208 offset:10880
	ds_read_b128 v[96:99], v208 offset:10752
	ds_read_b128 v[64:67], v207 offset:5376
	ds_read_b64 v[100:101], v209 offset:8704
	ds_read_b128 v[80:83], v208 offset:10944
	global_store_dword v[126:127], v156, off offset:-4096
	v_mfma_f32_16x16x32_bf16 v[146:149], v[130:133], v[0:3], v[134:137]
	global_store_dword v[102:103], v157, off offset:2048
	global_store_dword v[126:127], v158, off
	global_store_dword v[126:127], v159, off offset:2048
	s_waitcnt vmcnt(17)
	ds_write_b128 v181, v[32:35] offset:11008
	s_waitcnt vmcnt(16)
	ds_write_b128 v188, v[36:39] offset:11008
	v_mfma_f32_16x16x32_bf16 v[152:155], v[122:125], v[0:3], v[110:113]
	v_mfma_f32_16x16x32_bf16 v[158:161], v[118:121], v[0:3], v[106:109]
	s_and_saveexec_b64 s[12:13], s[42:43]
	ds_write_b128 v189, v[40:43] offset:11008
	s_or_b64 exec, exec, s[12:13]
	s_cmpk_gt_u32 s34, 0xf8
	s_cbranch_scc1 .LBB0_935
	v_add_co_u32_e32 v0, vcc, 0x4c59000, v176
	s_nop 1
	v_addc_co_u32_e32 v1, vcc, 0, v177, vcc
	v_add_co_u32_e32 v36, vcc, 0x4c5a000, v176
	s_nop 1
	v_addc_co_u32_e32 v37, vcc, 0, v177, vcc
	global_load_dwordx4 v[32:35], v[0:1], off offset:3328
	s_nop 0
	global_load_dwordx4 v[36:39], v[36:37], off offset:3328
	s_and_saveexec_b64 s[12:13], s[42:43]
	s_cbranch_execz .LBB0_934
	v_add_co_u32_e32 v0, vcc, 0x4c5b000, v176
	s_nop 1
	v_addc_co_u32_e32 v1, vcc, 0, v177, vcc
	global_load_dwordx4 v[40:43], v[0:1], off offset:3328

.LBB0_935:
	v_cvt_pk_bf16_f32 v108, v138, v139
	v_cvt_pk_bf16_f32 v109, v140, v141
	v_cvt_pk_bf16_f32 v110, v146, v147
	v_cvt_pk_bf16_f32 v111, v148, v149
	v_cvt_pk_bf16_f32 v122, v152, v153
	v_cvt_pk_bf16_f32 v123, v154, v155
	s_nop 0
	v_lshlrev_b32_e32 v0, 16, v108
	v_and_b32_e32 v1, 0xffff0000, v108
	v_sub_f32_e32 v0, v138, v0
	v_sub_f32_e32 v1, v139, v1
	v_cvt_pk_bf16_f32 v112, v0, v1
	v_lshlrev_b32_e32 v0, 16, v109
	v_and_b32_e32 v1, 0xffff0000, v109
	v_sub_f32_e32 v0, v140, v0
	v_sub_f32_e32 v1, v141, v1
	s_waitcnt lgkmcnt(14)
	v_mfma_f32_16x16x32_bf16 v[116:119], v[92:95], v[108:111], 0
	v_cvt_pk_bf16_f32 v113, v0, v1
	v_lshlrev_b32_e32 v0, 16, v110
	v_and_b32_e32 v1, 0xffff0000, v110
	v_sub_f32_e32 v0, v146, v0
	v_sub_f32_e32 v1, v147, v1
	v_cvt_pk_bf16_f32 v114, v0, v1
	v_lshlrev_b32_e32 v0, 16, v111
	v_and_b32_e32 v1, 0xffff0000, v111
	v_sub_f32_e32 v0, v148, v0
	v_sub_f32_e32 v1, v149, v1
	v_cvt_pk_bf16_f32 v115, v0, v1
	v_lshlrev_b32_e32 v0, 16, v122
	v_mfma_f32_16x16x32_bf16 v[116:119], v[92:95], v[112:115], v[116:119]
	v_and_b32_e32 v1, 0xffff0000, v122
	v_sub_f32_e32 v0, v152, v0
	v_sub_f32_e32 v1, v153, v1
	v_cvt_pk_bf16_f32 v126, v0, v1
	v_lshlrev_b32_e32 v0, 16, v123
	v_and_b32_e32 v1, 0xffff0000, v123
	v_cvt_pk_bf16_f32 v124, v158, v159
	v_cvt_pk_bf16_f32 v125, v160, v161
	v_sub_f32_e32 v0, v154, v0
	v_sub_f32_e32 v1, v155, v1
	s_waitcnt lgkmcnt(12)
	v_mfma_f32_16x16x32_bf16 v[116:119], v[88:91], v[122:125], v[116:119]
	v_cvt_pk_bf16_f32 v127, v0, v1
	v_lshlrev_b32_e32 v0, 16, v124
	v_and_b32_e32 v1, 0xffff0000, v124
	v_sub_f32_e32 v0, v158, v0
	v_sub_f32_e32 v1, v159, v1
	v_cvt_pk_bf16_f32 v128, v0, v1
	v_lshlrev_b32_e32 v0, 16, v125
	v_and_b32_e32 v1, 0xffff0000, v125
	v_mov_b32_e32 v106, v3
	v_mov_b32_e32 v107, v3
	v_sub_f32_e32 v0, v160, v0
	v_sub_f32_e32 v1, v161, v1
	v_cvt_pk_bf16_f32 v129, v0, v1
	v_mov_b32_e32 v102, v3
	v_mfma_f32_16x16x32_bf16 v[116:119], v[88:91], v[126:129], v[116:119]
	v_mov_b32_e32 v103, v3
	s_waitcnt lgkmcnt(3)
	v_mov_b32_e32 v216, v100
	v_mov_b32_e32 v217, v101
	v_mfma_f32_16x16x32_bf16 v[210:213], v[104:107], v[100:103], v[116:119]
	v_mul_f32_e64 v154, v70, v154
	v_mul_f32_e64 v155, v71, v155
	v_pk_mul_f32 v[152:153], v[68:69], v[152:153]
	s_waitcnt lgkmcnt(2)
	v_pk_mul_f32 v[160:161], v[82:83], v[160:161]
	v_mfma_f32_16x16x32_bf16 v[106:109], v[76:79], v[108:111], 0
	v_mul_f32_e64 v158, v80, v158
	v_mul_f32_e64 v159, v81, v159
	s_waitcnt lgkmcnt(0)
	s_barrier
	v_mfma_f32_16x16x32_bf16 v[106:109], v[76:79], v[112:115], v[106:109]
	ds_read_b128 v[118:121], v204 offset:11008
	ds_read_b128 v[170:173], v204 offset:13056
	ds_read_b128 v[134:137], v205 offset:11008
	ds_read_b128 v[162:165], v205 offset:13056
	s_mov_b32 s12, 0x1bf17000
	v_mfma_f32_16x16x32_bf16 v[122:125], v[72:75], v[122:125], v[106:109]
	ds_read_b64 v[150:151], v206 offset:15104
	ds_read_b128 v[114:117], v207 offset:15616
	ds_read_b128 v[110:113], v207 offset:15872
	ds_read_b128 v[106:109], v207 offset:16128
	v_add_co_u32_e32 v102, vcc, s12, v186
	v_mfma_f32_16x16x32_bf16 v[122:125], v[72:75], v[126:129], v[122:125]
	v_mul_f32_e64 v128, v98, v140
	v_mul_f32_e64 v129, v99, v141
	v_pk_mul_f32 v[126:127], v[96:97], v[138:139]
	ds_read_b128 v[138:141], v208 offset:21824
	ds_read_b128 v[130:133], v208 offset:21888
	v_addc_co_u32_e32 v103, vcc, 0, v187, vcc
	s_nop 1
	v_xor_b32_e32 v0, 0x80000000, v122
	v_xor_b32_e32 v1, 0x80000000, v123
	v_cvt_pk_bf16_f32 v214, v0, v1
	v_xor_b32_e32 v0, 0x80000000, v124
	v_xor_b32_e32 v1, 0x80000000, v125
	v_cvt_pk_bf16_f32 v215, v0, v1
	v_lshlrev_b32_e32 v0, 16, v214
	v_and_b32_e32 v1, 0xffff0000, v214
	v_sub_f32_e64 v0, -v122, v0
	v_sub_f32_e64 v1, -v123, v1
	v_mfma_f32_16x16x32_bf16 v[126:129], v[60:63], v[214:217], v[126:129]
	v_cvt_pk_bf16_f32 v0, v0, v1
	v_lshlrev_b32_e32 v1, 16, v215
	v_and_b32_e32 v2, 0xffff0000, v215
	v_sub_f32_e64 v1, -v124, v1
	v_sub_f32_e64 v2, -v125, v2
	v_pk_mul_f32 v[124:125], v[86:87], v[148:149]
	v_pk_mul_f32 v[122:123], v[84:85], v[146:147]
	v_cvt_pk_bf16_f32 v1, v1, v2
	v_mov_b32_e32 v2, v3
	v_mfma_f32_16x16x32_bf16 v[152:155], v[52:55], v[214:217], v[152:155]
	s_mov_b32 s12, 0x1bf18000
	s_cmpk_lt_u32 s34, 0xfc
	v_add_co_u32_e32 v218, vcc, s12, v186
	v_mfma_f32_16x16x32_bf16 v[146:149], v[56:59], v[214:217], v[122:125]
	s_cselect_b64 s[12:13], -1, 0
	s_cmpk_gt_u32 s34, 0xfb
	v_addc_co_u32_e32 v219, vcc, 0, v187, vcc
	v_mfma_f32_16x16x32_bf16 v[158:161], v[64:67], v[214:217], v[158:161]
	s_cselect_b64 s[40:41], -1, 0
	s_and_b64 vcc, exec, s[40:41]
	v_mfma_f32_16x16x32_bf16 v[142:145], v[60:63], v[0:3], v[126:129]
	ds_read_b128 v[166:169], v208 offset:21760
	ds_read_b128 v[122:125], v207 offset:16384
	ds_read_b64 v[174:175], v209 offset:19712
	ds_read_b128 v[126:129], v208 offset:21952
	global_store_dword v[218:219], v210, off offset:-4096
	global_store_dword v[102:103], v211, off offset:2048
	global_store_dword v[218:219], v212, off
	global_store_dword v[218:219], v213, off offset:2048
	v_mfma_f32_16x16x32_bf16 v[146:149], v[56:59], v[0:3], v[146:149]
	v_mfma_f32_16x16x32_bf16 v[154:157], v[52:55], v[0:3], v[152:155]
	v_mfma_f32_16x16x32_bf16 v[158:161], v[64:67], v[0:3], v[158:161]
	s_cbranch_vccnz .LBB0_939
	s_waitcnt vmcnt(23)
	ds_write_b128 v181, v[44:47]
	s_waitcnt vmcnt(22)
	ds_write_b128 v188, v[48:51]
	s_and_saveexec_b64 s[50:51], s[42:43]
	ds_write_b128 v189, v[4:7]
	s_or_b64 exec, exec, s[50:51]
.LBB0_939:
	s_cmpk_gt_u32 s34, 0xf7
	s_cbranch_scc1 .LBB0_943
	v_add_co_u32_e32 v0, vcc, 0x4c5c000, v176
	s_nop 1
	v_addc_co_u32_e32 v1, vcc, 0, v177, vcc
	s_waitcnt vmcnt(22)
	v_add_co_u32_e32 v48, vcc, 0x4c5d000, v176
	s_nop 1
	v_addc_co_u32_e32 v49, vcc, 0, v177, vcc
	global_load_dwordx4 v[44:47], v[0:1], off offset:2048
	s_nop 0
	global_load_dwordx4 v[48:51], v[48:49], off offset:2048
	s_and_saveexec_b64 s[50:51], s[42:43]
	s_cbranch_execz .LBB0_942
	v_add_co_u32_e32 v0, vcc, 0x4c5e000, v176
	s_nop 1
	v_addc_co_u32_e32 v1, vcc, 0, v177, vcc
	global_load_dwordx4 v[4:7], v[0:1], off offset:2048
